# MLA tile loops: PV MFMAs of query group 0 issued beside the exps of group 1 (P0 in v246-253, four V fragments read up front); on top of NSA chunk pipelining
# baseline (speedup 1.0000x reference)
; #define LAS __attribute__((address_space(3)))
; DI float fexp2(float x) { return __builtin_amdgcn_exp2f(x); }
; DI f32x16 mfma32(bf16x8 a, bf16x8 b, f32x16 c) { return __builtin_amdgcn_mfma_f32_32x32x16_bf16(a, b, c, 0, 0, 0); }
; DI void softmax_lazy1(f32x16& s, float& m, float& l, f32x16 (&o)[2], int hh) {
;     ...
; #pragma unroll
;     for (int i = 0; i < 16; ++i) { s[i] = fexp2(s[i]); sum += s[i]; }
;     sum += __shfl_xor(sum, 32);
;     l += sum;
; DI void pv_sub2(const LAS unsigned char* vt, int vstride, int koff_bytes, const f32x16& p0, const f32x16& p1, f32x16 (&o0)[2], f32x16 (&o1)[2], int r, int hh) {
; #pragma unroll
;     for (int st = 0; st < 2; ++st) {
;         u32x2 lo[2], hi[2];
; #pragma unroll
;         for (int u = 0; u < 2; ++u) {
;             const LAS unsigned char* a = vt + (32 * u + r) * vstride + koff_bytes + 32 * st + 8 * hh;
;             lo[u] = *(const LAS u32x2*)a; hi[u] = *(const LAS u32x2*)(a + 16);
;         }
;         const bf16x8 pf0 = st ? pack8<1>(p0) : pack8<0>(p0), pf1 = st ? pack8<1>(p1) : pack8<0>(p1);
;         __builtin_amdgcn_sched_barrier(0);
; #pragma unroll
;         for (int u = 0; u < 2; ++u) { u32x4 v; v.x = lo[u].x; v.y = lo[u].y; v.z = hi[u].x; v.w = hi[u].y; const bf16x8 vf = __builtin_bit_cast(bf16x8, v);
;             o0[u] = mfma32(vf, pf0, o0[u]); o1[u] = mfma32(vf, pf1, o1[u]); }
;     }
; }
.LBB0_2827:
	v_add_f32_e32 v0, v211, v212
	v_add_f32_e32 v200, v200, v0
	v_cvt_pk_bf16_f32 v246, v84, v85
	v_cvt_pk_bf16_f32 v247, v86, v87
	v_cvt_pk_bf16_f32 v248, v88, v89
	v_cvt_pk_bf16_f32 v249, v90, v91
	v_cvt_pk_bf16_f32 v250, v92, v93
	v_cvt_pk_bf16_f32 v251, v94, v95
	v_cvt_pk_bf16_f32 v252, v96, v97
	v_cvt_pk_bf16_f32 v253, v98, v99
	v_lshl_add_u32 v0, s48, 6, v210
	v_add_u32_e32 v2, 0x3000, v0
	v_add_u32_e32 v0, 0x4000, v0
	ds_read2_b64 v[84:87], v2 offset0:128 offset1:130
	ds_read2_b64 v[88:91], v0 offset0:160 offset1:162
	ds_read2_b64 v[92:95], v2 offset0:132 offset1:134
	ds_read2_b64 v[96:99], v0 offset0:164 offset1:166
	s_xor_b64 s[4:5], s[22:23], -1
	v_exp_f32_e32 v0, v68
	v_exp_f32_e32 v3, v69
	v_exp_f32_e32 v211, v70
	v_exp_f32_e32 v212, v71
	v_add_f32_e32 v2, 0, v0
	v_exp_f32_e32 v213, v72
	v_add_f32_e32 v2, v3, v2
	v_exp_f32_e32 v214, v73
	v_add_f32_e32 v2, v211, v2
	v_exp_f32_e32 v215, v74
	v_add_f32_e32 v2, v212, v2
	s_waitcnt lgkmcnt(2)
	v_mfma_f32_32x32x16_bf16 v[4:19], v[84:87], v[246:249], v[4:19]
	v_exp_f32_e32 v216, v75
	v_add_f32_e32 v2, v213, v2
	v_exp_f32_e32 v76, v76
	v_add_f32_e32 v2, v214, v2
	v_exp_f32_e32 v77, v77
	v_mfma_f32_32x32x16_bf16 v[20:35], v[88:91], v[246:249], v[20:35]
	v_add_f32_e32 v2, v215, v2
	v_exp_f32_e32 v78, v78
	v_add_f32_e32 v2, v216, v2
	v_exp_f32_e32 v79, v79
	v_add_f32_e32 v2, v76, v2
	s_waitcnt lgkmcnt(0)
	v_mfma_f32_32x32x16_bf16 v[4:19], v[92:95], v[250:253], v[4:19]
	v_exp_f32_e32 v80, v80
	v_add_f32_e32 v2, v77, v2
	v_exp_f32_e32 v81, v81
	v_add_f32_e32 v2, v78, v2
	v_exp_f32_e32 v82, v82
	v_mfma_f32_32x32x16_bf16 v[20:35], v[96:99], v[250:253], v[20:35]
	v_add_f32_e32 v2, v79, v2
	v_exp_f32_e32 v83, v83
	v_add_f32_e32 v2, v80, v2
	v_add_f32_e32 v2, v81, v2
	v_add_f32_e32 v2, v82, v2
	v_add_f32_e32 v2, v83, v2
	v_mov_b32_e32 v68, v2
	v_cvt_pk_bf16_f32 v76, v76, v77
	v_cvt_pk_bf16_f32 v77, v78, v79
	v_cvt_pk_bf16_f32 v78, v80, v81
	v_cvt_pk_bf16_f32 v80, v0, v3
	v_permlane32_swap_b32_e32 v68, v2
	v_add_f32_e32 v2, v2, v68
	v_add_f32_e32 v196, v196, v2
	v_cvt_pk_bf16_f32 v79, v82, v83
	v_cvt_pk_bf16_f32 v81, v211, v212
	v_cvt_pk_bf16_f32 v82, v213, v214
	v_cvt_pk_bf16_f32 v83, v215, v216
	s_mov_b32 s48, 1
	s_mov_b64 s[22:23], 0
	s_and_b64 vcc, exec, s[4:5]
	v_mfma_f32_32x32x16_bf16 v[52:67], v[84:87], v[80:83], v[52:67]
	v_mfma_f32_32x32x16_bf16 v[36:51], v[88:91], v[80:83], v[36:51]
	v_mfma_f32_32x32x16_bf16 v[52:67], v[92:95], v[76:79], v[52:67]
	v_mfma_f32_32x32x16_bf16 v[36:51], v[96:99], v[76:79], v[36:51]
	s_cbranch_vccnz .LBB0_2844

; #define LAS __attribute__((address_space(3)))
; DI float fexp2(float x) { return __builtin_amdgcn_exp2f(x); }
; DI f32x16 mfma32(bf16x8 a, bf16x8 b, f32x16 c) { return __builtin_amdgcn_mfma_f32_32x32x16_bf16(a, b, c, 0, 0, 0); }
; DI void softmax_lazy1(f32x16& s, float& m, float& l, f32x16 (&o)[2], int hh) {
;     ...
; #pragma unroll
;     for (int i = 0; i < 16; ++i) { s[i] = fexp2(s[i]); sum += s[i]; }
;     sum += __shfl_xor(sum, 32);
;     l += sum;
; DI void pv_sub2(const LAS unsigned char* vt, int vstride, int koff_bytes, const f32x16& p0, const f32x16& p1, f32x16 (&o0)[2], f32x16 (&o1)[2], int r, int hh) {
; #pragma unroll
;     for (int st = 0; st < 2; ++st) {
;         u32x2 lo[2], hi[2];
; #pragma unroll
;         for (int u = 0; u < 2; ++u) {
;             const LAS unsigned char* a = vt + (32 * u + r) * vstride + koff_bytes + 32 * st + 8 * hh;
;             lo[u] = *(const LAS u32x2*)a; hi[u] = *(const LAS u32x2*)(a + 16);
;         }
;         const bf16x8 pf0 = st ? pack8<1>(p0) : pack8<0>(p0), pf1 = st ? pack8<1>(p1) : pack8<0>(p1);
;         __builtin_amdgcn_sched_barrier(0);
; #pragma unroll
;         for (int u = 0; u < 2; ++u) { u32x4 v; v.x = lo[u].x; v.y = lo[u].y; v.z = hi[u].x; v.w = hi[u].y; const bf16x8 vf = __builtin_bit_cast(bf16x8, v);
;             o0[u] = mfma32(vf, pf0, o0[u]); o1[u] = mfma32(vf, pf1, o1[u]); }
;     }
; }
.LBB0_2859:
	v_add_f32_e32 v0, v169, v170
	v_add_f32_e32 v200, v200, v0
	v_cvt_pk_bf16_f32 v246, v68, v69
	v_cvt_pk_bf16_f32 v247, v70, v71
	v_cvt_pk_bf16_f32 v248, v72, v73
	v_cvt_pk_bf16_f32 v249, v74, v75
	v_cvt_pk_bf16_f32 v250, v76, v77
	v_cvt_pk_bf16_f32 v251, v78, v79
	v_cvt_pk_bf16_f32 v252, v80, v81
	v_cvt_pk_bf16_f32 v253, v82, v83
	v_lshl_add_u32 v2, s46, 6, v167
	v_add_u32_e32 v0, v2, v197
	v_add_u32_e32 v2, v2, v198
	v_add_u32_e32 v0, 0x3000, v0
	v_add_u32_e32 v2, 0x3000, v2
	ds_read2_b64 v[68:71], v0 offset0:128 offset1:130
	ds_read2_b64 v[72:75], v2 offset0:128 offset1:130
	ds_read2_b64 v[76:79], v0 offset0:132 offset1:134
	ds_read2_b64 v[80:83], v2 offset0:132 offset1:134
	s_xor_b64 s[4:5], s[22:23], -1
	v_exp_f32_e32 v0, v84
	v_exp_f32_e32 v3, v85
	v_exp_f32_e32 v84, v86
	v_exp_f32_e32 v85, v87
	v_add_f32_e32 v2, 0, v0
	v_exp_f32_e32 v86, v88
	v_add_f32_e32 v2, v3, v2
	v_exp_f32_e32 v87, v89
	v_add_f32_e32 v2, v84, v2
	v_exp_f32_e32 v88, v90
	v_add_f32_e32 v2, v85, v2
	s_waitcnt lgkmcnt(2)
	v_mfma_f32_32x32x16_bf16 v[4:19], v[68:71], v[246:249], v[4:19]
	v_exp_f32_e32 v89, v91
	v_add_f32_e32 v2, v86, v2
	v_exp_f32_e32 v90, v92
	v_add_f32_e32 v2, v87, v2
	v_exp_f32_e32 v91, v93
	v_mfma_f32_32x32x16_bf16 v[20:35], v[72:75], v[246:249], v[20:35]
	v_add_f32_e32 v2, v88, v2
	v_exp_f32_e32 v92, v94
	v_add_f32_e32 v2, v89, v2
	v_exp_f32_e32 v93, v95
	v_add_f32_e32 v2, v90, v2
	s_waitcnt lgkmcnt(0)
	v_mfma_f32_32x32x16_bf16 v[4:19], v[76:79], v[250:253], v[4:19]
	v_exp_f32_e32 v94, v96
	v_add_f32_e32 v2, v91, v2
	v_exp_f32_e32 v95, v97
	v_add_f32_e32 v2, v92, v2
	v_exp_f32_e32 v96, v98
	v_mfma_f32_32x32x16_bf16 v[20:35], v[80:83], v[250:253], v[20:35]
	v_add_f32_e32 v2, v93, v2
	v_exp_f32_e32 v97, v99
	v_add_f32_e32 v2, v94, v2
	v_add_f32_e32 v2, v95, v2
	v_add_f32_e32 v2, v96, v2
	v_add_f32_e32 v2, v97, v2
	v_mov_b32_e32 v98, v2
	s_nop 1
	v_permlane32_swap_b32_e32 v98, v2
	v_add_f32_e32 v2, v2, v98
	v_add_f32_e32 v196, v196, v2
	v_cvt_pk_bf16_f32 v246, v0, v3
	v_cvt_pk_bf16_f32 v247, v84, v85
	v_cvt_pk_bf16_f32 v248, v86, v87
	v_cvt_pk_bf16_f32 v249, v88, v89
	v_cvt_pk_bf16_f32 v250, v90, v91
	v_cvt_pk_bf16_f32 v251, v92, v93
	v_cvt_pk_bf16_f32 v252, v94, v95
	v_cvt_pk_bf16_f32 v253, v96, v97
	s_mov_b32 s46, 1
	s_mov_b64 s[22:23], 0
	s_andn2_b64 vcc, exec, s[4:5]
	v_mfma_f32_32x32x16_bf16 v[52:67], v[68:71], v[246:249], v[52:67]
	v_mfma_f32_32x32x16_bf16 v[36:51], v[72:75], v[246:249], v[36:51]
	v_mfma_f32_32x32x16_bf16 v[52:67], v[76:79], v[250:253], v[52:67]
	v_mfma_f32_32x32x16_bf16 v[36:51], v[80:83], v[250:253], v[36:51]
	s_cbranch_vccz .LBB0_2876
